# P4 chunk prologue: scratch-independent operand loads issued before the LoRA scratch stage; LoRA A-operand scratch through LDS (ds_write_b16 / ds_read_b128 + barrier) instead of global store-drain, cac
# speedup vs baseline: 1.0181x; 1.0181x over previous
; __device__ __forceinline__ void rwkv_phase_a(const Ctx& C) {
;     ...
;       bf16x8 Af[4][2], Bf[4][2][2]; bf16_t zn[3][9];
;       {
;           int tid = C.tid; asm volatile("" : "+v"(tid));
;           const int lane = tid & 63, q = lane >> 4, l15 = lane & 15, mrow = mt * 16 + l15, nc0 = nt0 * 16 + l15, ci = tid & 63, tokb = tok0 + (tid >> 6) * 8;
; #pragma unroll
;           for (int g = 0; g < 4; ++g)
; #pragma unroll
;               for (int ks = 0; ks < 2; ++ks) Af[g][ks] = *(const bf16x8*)(scrg + (size_t)mrow * 256 + g * 64 + ks * 32 + q * 8);
; #pragma unroll
;           for (int ks = 0; ks < 2; ++ks)
; #pragma unroll
;               for (int i = 0; i < 2; ++i) { const int row = nc0 + 16 * i;
;                   Bf[0][ks][i] = *(const bf16x8*)(wdecT + (size_t)row * 64 + ks * 32 + q * 8); Bf[1][ks][i] = *(const bf16x8*)(waaaT + (size_t)row * 64 + ks * 32 + q * 8);
;                   Bf[2][ks][i] = *(const bf16x8*)(wgateT + (size_t)row * 128 + ks * 32 + q * 8); Bf[3][ks][i] = *(const bf16x8*)(wgateT + (size_t)row * 128 + 64 + ks * 32 + q * 8); }
;           zload9(zr, tokb, ci, zn[0]); zload9(zr, tokb, 512 + ci, zn[1]); zload9(zr, tokb, 1024 + ci, zn[2]);
.LBB0_715:
	s_lshl_b32 s71, s16, 6
	v_mov_b32_e32 v1, v0
	v_readlane_b32 s14, v253, 4
	v_and_b32_e32 v34, 15, v1
	v_or_b32_e32 v188, s3, v34
	v_ashrrev_i32_e32 v2, 3, v1
	v_and_b32_e32 v47, -8, v2
	v_and_b32_e32 v188, 48, v1
	v_readlane_b32 s15, v253, 5
	v_and_b32_e32 v46, 63, v1
	v_or_b32_e32 v1, s56, v34
	v_lshl_add_u64 v[34:35], s[14:15], 0, v[188:189]
	v_readlane_b32 s14, v253, 6
	v_readlane_b32 s15, v253, 7
	v_lshlrev_b32_e32 v38, 7, v1
	v_mov_b32_e32 v39, v189
	v_lshlrev_b32_e32 v42, 8, v1
	v_mov_b32_e32 v43, v189
	v_or_b32_e32 v1, 16, v1
	v_lshl_add_u64 v[36:37], s[14:15], 0, v[188:189]
	v_lshl_add_u64 v[40:41], v[34:35], 0, v[38:39]
	v_lshl_add_u64 v[42:43], s[12:13], 0, v[42:43]
	v_lshlrev_b32_e32 v44, 7, v1
	v_mov_b32_e32 v45, v189
	s_nop 0
	v_lshl_add_u64 v[38:39], v[36:37], 0, v[38:39]
	v_lshl_add_u64 v[42:43], v[42:43], 0, v[188:189]
	v_lshl_add_u64 v[34:35], v[34:35], 0, v[44:45]
	global_load_dwordx4 v[98:101], v[40:41], off
	global_load_dwordx4 v[106:109], v[40:41], off offset:64
	global_load_dwordx4 v[110:113], v[38:39], off
	global_load_dwordx4 v[114:117], v[38:39], off offset:64
	global_load_dwordx4 v[118:121], v[42:43], off
	global_load_dwordx4 v[122:125], v[42:43], off offset:64
	global_load_dwordx4 v[126:129], v[42:43], off offset:128
	global_load_dwordx4 v[130:133], v[42:43], off offset:192
	global_load_dwordx4 v[138:141], v[34:35], off
	global_load_dwordx4 v[142:145], v[34:35], off offset:64
	v_lshl_add_u64 v[36:37], v[36:37], 0, v[44:45]
	v_lshlrev_b32_e32 v44, 8, v1
	v_lshl_add_u64 v[44:45], s[12:13], 0, v[44:45]
	v_lshl_add_u64 v[44:45], v[44:45], 0, v[188:189]
	v_add_u32_e32 v1, s71, v47
	v_lshlrev_b32_e32 v188, 1, v46
	v_lshl_add_u64 v[38:39], s[26:27], 0, v[188:189]
	v_or_b32_e32 v52, 5, v1
	v_mad_i64_i32 v[52:53], s[14:15], v52, s0, v[38:39]
	v_or_b32_e32 v54, 6, v1
	v_mad_i64_i32 v[54:55], s[14:15], v54, s0, v[38:39]
	global_load_ushort v56, v[52:53], off
	global_load_ushort v57, v[54:55], off
	v_max_i32_e32 v34, 1, v1
	v_add_u32_e32 v34, -1, v34
	v_mad_u64_u32 v[34:35], s[14:15], v34, s0, v[186:187]
	v_mad_i64_i32 v[40:41], s[14:15], v1, s0, v[38:39]
	v_or_b32_e32 v42, 1, v1
	v_or_b32_e32 v46, 2, v1
	v_or_b32_e32 v48, 3, v1
	v_or_b32_e32 v50, 4, v1
	v_or_b32_e32 v1, 7, v1
	v_lshl_add_u64 v[34:35], v[34:35], 0, v[188:189]
	v_mad_i64_i32 v[42:43], s[14:15], v42, s0, v[38:39]
	v_mad_i64_i32 v[46:47], s[14:15], v46, s0, v[38:39]
	v_mad_i64_i32 v[48:49], s[14:15], v48, s0, v[38:39]
	v_mad_i64_i32 v[50:51], s[14:15], v50, s0, v[38:39]
	v_mad_i64_i32 v[38:39], s[14:15], v1, s0, v[38:39]
	global_load_ushort v68, v[38:39], off
	global_load_ushort v58, v[38:39], off offset:1024
	global_load_ushort v59, v[34:35], off
	global_load_ushort v60, v[40:41], off
	global_load_ushort v61, v[42:43], off
	global_load_ushort v62, v[34:35], off offset:1024
	global_load_ushort v63, v[40:41], off offset:1024
	global_load_ushort v64, v[42:43], off offset:1024
	s_nop 0
	global_load_ushort v71, v[40:41], off offset:2048
	s_nop 0
	global_load_ushort v69, v[34:35], off offset:2048
	s_nop 0
	global_load_ushort v70, v[46:47], off
	global_load_ushort v72, v[48:49], off
	global_load_ushort v65, v[50:51], off
	global_load_ushort v66, v[46:47], off offset:1024
	global_load_ushort v67, v[48:49], off offset:1024
	s_nop 0
	global_load_ushort v48, v[48:49], off offset:2048
	s_nop 0
	global_load_ushort v75, v[46:47], off offset:2048
	s_nop 0
	global_load_ushort v73, v[42:43], off offset:2048
	s_nop 0
	global_load_ushort v74, v[50:51], off offset:1024
	global_load_ushort v47, v[52:53], off offset:1024
	global_load_ushort v49, v[54:55], off offset:1024
	s_nop 0
	global_load_ushort v54, v[54:55], off offset:2048
	s_nop 0
	global_load_ushort v52, v[52:53], off offset:2048
	s_nop 0
	global_load_ushort v50, v[50:51], off offset:2048
	s_nop 0
	global_load_dwordx4 v[158:161], v[36:37], off
	global_load_dwordx4 v[162:165], v[36:37], off offset:64
	global_load_dwordx4 v[166:169], v[44:45], off
	global_load_dwordx4 v[170:173], v[44:45], off offset:64
	global_load_dwordx4 v[174:177], v[44:45], off offset:128
	global_load_dwordx4 v[178:181], v[44:45], off offset:192
	global_load_ushort v214, v[38:39], off offset:2048
	v_mov_b32_e32 v1, v0
	s_lshl_b32 s71, s16, 6
	v_and_b32_e32 v20, 63, v1
	v_ashrrev_i32_e32 v1, 3, v1
	v_and_b32_e32 v21, -8, v1
	v_add_u32_e32 v22, s71, v21
	v_max_i32_e32 v2, 1, v22
	v_readlane_b32 s40, v254, 6
	v_add_u32_e32 v14, -1, v2
	v_lshlrev_b32_e32 v188, 1, v20
	v_readlane_b32 s42, v254, 8
	v_readlane_b32 s43, v254, 9
	v_readlane_b32 s52, v254, 18
	v_readlane_b32 s53, v254, 19
	v_readlane_b32 s54, v254, 20
	v_readlane_b32 s55, v254, 21
	s_waitcnt lgkmcnt(0)
; __device__ __forceinline__ float bf2f(bf16_t b) { return __uint_as_float(((unsigned)b) << 16); }
; __device__ __forceinline__ bf16_t f2bf(float f) { return (bf16_t)(pk2(f, 0.f) & 0xffffu); }
; __device__ __forceinline__ float sigmoidf_(float x) { return frcp(1.0f + __expf(-x)); }
; __device__ __forceinline__ float tanhf_(float x) { return 1.0f - 2.0f * frcp(1.0f + __expf(2.0f * x)); }
; __device__ __forceinline__ void zmix8(const bf16_t (&raw)[9], float pz, float mu, float (&o)[8]) {
;     float prv = bf2f(raw[0]) * pz;
; #pragma unroll
;     for (int u = 0; u < 8; ++u) { const float cur = bf2f(raw[u + 1]); o[u] = cur + (prv - cur) * mu; prv = cur; }
; }
; __device__ __forceinline__ void rwkv_phase_a(const Ctx& C) {
;     ...
;           int tid = C.tid; asm volatile("" : "+v"(tid));
;           const int ci = tid & 63, tg8 = tid >> 6, tokb = tok0 + tg8 * 8;
;           bf16_t r0[9], r1[9], r2[9], r3[9];
;           zload9(zr, tokb, 1536 + ci, r0); zload9(zr, tokb, 1600 + ci, r1); zload9(zr, tokb, 1664 + ci, r2); zload9(zr, tokb, 1728 + ci, r3);
;           const float m0 = mu[1536 + ci], m1 = mu[1600 + ci], m2 = mu[1664 + ci], m3 = mu[1728 + ci];
;           const float pz = tokb > 0 ? 1.f : 0.f;
;           float t8[8];
;           zmix8(r0, pz, m0, t8);
; #pragma unroll
;           for (int u = 0; u < 8; ++u) scrg[(tg8 * 8 + u) * 256 + ci] = f2bf(tanhf_(t8[u]));
;           zmix8(r1, pz, m1, t8);
; #pragma unroll
;           for (int u = 0; u < 8; ++u) scrg[(tg8 * 8 + u) * 256 + 64 + ci] = f2bf(t8[u]);
;           zmix8(r2, pz, m2, t8);
; #pragma unroll
;           for (int u = 0; u < 8; ++u) scrg[(tg8 * 8 + u) * 256 + 128 + ci] = f2bf(sigmoidf_(t8[u]));
;           zmix8(r3, pz, m3, t8);
; #pragma unroll
;           for (int u = 0; u < 8; ++u) scrg[(tg8 * 8 + u) * 256 + 192 + ci] = f2bf(sigmoidf_(t8[u]));
	v_lshl_add_u64 v[2:3], s[26:27], 0, v[188:189]
	v_mad_u64_u32 v[14:15], s[14:15], v14, s0, v[186:187]
	v_lshlrev_b32_e32 v28, 2, v20
	v_readlane_b32 s41, v254, 7
	s_mov_b64 s[54:55], s[42:43]
	v_mad_i64_i32 v[4:5], s[14:15], v22, s0, v[2:3]
	v_or_b32_e32 v6, 1, v22
	v_or_b32_e32 v8, 2, v22
	v_or_b32_e32 v10, 3, v22
	v_or_b32_e32 v12, 4, v22
	v_lshl_add_u64 v[14:15], v[14:15], 0, v[188:189]
	v_or_b32_e32 v16, 0x1800, v28
	s_mov_b64 s[52:53], s[40:41]
	v_mad_i64_i32 v[6:7], s[14:15], v6, s0, v[2:3]
	v_mad_i64_i32 v[8:9], s[14:15], v8, s0, v[2:3]
	v_mad_i64_i32 v[10:11], s[14:15], v10, s0, v[2:3]
	v_mad_i64_i32 v[12:13], s[14:15], v12, s0, v[2:3]
	global_load_ushort v23, v[4:5], off offset:3072
	global_load_ushort v24, v[6:7], off offset:3072
	global_load_ushort v25, v[8:9], off offset:3072
	global_load_ushort v26, v[10:11], off offset:3072
	global_load_ushort v27, v[12:13], off offset:3072
	global_load_ushort v29, v[14:15], off offset:3072
	global_load_dword v30, v16, s[52:53]
	v_or_b32_e32 v16, 5, v22
	v_mad_i64_i32 v[16:17], s[14:15], v16, s0, v[2:3]
	v_or_b32_e32 v18, 6, v22
	global_load_ushort v31, v[16:17], off offset:3072
	v_mad_i64_i32 v[18:19], s[14:15], v18, s0, v[2:3]
	global_load_ushort v32, v[18:19], off offset:3072
	v_or_b32_e32 v33, 7, v22
	v_mad_i64_i32 v[2:3], s[14:15], v33, s0, v[2:3]
	global_load_ushort v33, v[2:3], off offset:3072
	v_or_b32_e32 v34, 0x1900, v28
	v_or_b32_e32 v35, 0x1a00, v28
	v_or_b32_e32 v28, 0x1b00, v28
	global_load_dword v34, v34, s[52:53]
	s_nop 0
	global_load_dword v35, v35, s[52:53]
	s_nop 0
	global_load_dword v28, v28, s[52:53]
	s_nop 0
	global_load_ushort v36, v[6:7], off offset:3200
	global_load_ushort v37, v[8:9], off offset:3200
	global_load_ushort v38, v[6:7], off offset:3328
	global_load_ushort v39, v[8:9], off offset:3328
	s_nop 0
	global_load_ushort v8, v[8:9], off offset:3456
	s_nop 0
	global_load_ushort v6, v[6:7], off offset:3456
	s_nop 0
	global_load_ushort v7, v[10:11], off offset:3200
	global_load_ushort v9, v[12:13], off offset:3200
	global_load_ushort v40, v[10:11], off offset:3328
	global_load_ushort v41, v[12:13], off offset:3328
	s_nop 0
	global_load_ushort v12, v[12:13], off offset:3456
	s_nop 0
	global_load_ushort v10, v[10:11], off offset:3456
	s_nop 0
	global_load_ushort v11, v[4:5], off offset:3200
	global_load_ushort v13, v[4:5], off offset:3328
	global_load_ushort v42, v[4:5], off offset:3456
	global_load_ushort v43, v[14:15], off offset:3200
	global_load_ushort v44, v[14:15], off offset:3328
	s_nop 0
	global_load_ushort v14, v[14:15], off offset:3456
	v_cmp_lt_i32_e32 vcc, 0, v22
	v_writelane_b32 v253, s16, 16
	v_lshlrev_b32_e32 v1, 8, v1
	v_cndmask_b32_e64 v22, 0, 1.0, vcc
	v_readlane_b32 s16, v253, 8
	v_readlane_b32 s17, v253, 9
	s_movk_i32 s14, 0x700
	s_mov_b64 s[18:19], 0
	s_mov_b32 s72, 0
	v_readlane_b32 s44, v254, 10
	v_readlane_b32 s45, v254, 11
	v_readlane_b32 s46, v254, 12
	v_readlane_b32 s47, v254, 13
	v_readlane_b32 s48, v254, 14
	v_readlane_b32 s49, v254, 15
	v_readlane_b32 s50, v254, 16
	v_readlane_b32 s51, v254, 17
	s_waitcnt vmcnt(30)
	v_lshlrev_b32_e32 v4, 16, v23
	s_waitcnt vmcnt(29)
	v_lshlrev_b32_e32 v5, 16, v24
	s_waitcnt vmcnt(28)
	v_lshlrev_b32_e32 v15, 16, v25
	s_waitcnt vmcnt(27)
	v_lshlrev_b32_e32 v23, 16, v26
	v_sub_f32_e32 v25, v4, v5
	s_waitcnt vmcnt(25)
	v_lshlrev_b32_e32 v29, 16, v29
	v_lshlrev_b32_e32 v24, 16, v27
	v_sub_f32_e32 v26, v5, v15
	v_sub_f32_e32 v27, v15, v23
	s_waitcnt vmcnt(24)
	v_fmac_f32_e32 v5, v25, v30
	v_fma_f32 v25, v22, v29, -v4
	v_sub_f32_e32 v45, v23, v24
	v_fmac_f32_e32 v15, v26, v30
	v_fmac_f32_e32 v23, v27, v30
	v_fmac_f32_e32 v4, v25, v30
	global_load_ushort v25, v[16:17], off offset:3200
	global_load_ushort v26, v[18:19], off offset:3200
	global_load_ushort v27, v[16:17], off offset:3328
	global_load_ushort v29, v[18:19], off offset:3328
	s_nop 0
	global_load_ushort v18, v[18:19], off offset:3456
	s_nop 0
	global_load_ushort v16, v[16:17], off offset:3456
	s_waitcnt vmcnt(29)
	v_lshlrev_b32_e32 v17, 16, v31
	v_sub_f32_e32 v19, v24, v17
	s_waitcnt vmcnt(28)
	v_lshlrev_b32_e32 v31, 16, v32
	v_fmac_f32_e32 v24, v45, v30
	v_sub_f32_e32 v32, v17, v31
	v_fmac_f32_e32 v17, v19, v30
	global_load_ushort v19, v[2:3], off offset:3200
	global_load_ushort v45, v[2:3], off offset:3328
	global_load_ushort v46, v[2:3], off offset:3456
	v_add_f32_e32 v2, v4, v4
	v_mul_f32_e32 v2, 0x3fb8aa3b, v2
	s_waitcnt vmcnt(30)
	v_lshlrev_b32_e32 v33, 16, v33
	v_exp_f32_e32 v2, v2
	v_sub_f32_e32 v3, v31, v33
	v_fmac_f32_e32 v33, v3, v30
	v_add_f32_e32 v3, v5, v5
	v_mul_f32_e32 v3, 0x3fb8aa3b, v3
	v_add_f32_e32 v2, 1.0, v2
	v_exp_f32_e32 v3, v3
	v_rcp_f32_e32 v2, v2
	v_fmac_f32_e32 v31, v32, v30
	s_waitcnt vmcnt(14)
	v_lshlrev_b32_e32 v11, 16, v11
	v_add_f32_e32 v3, 1.0, v3
	v_fma_f32 v2, v2, -2.0, 1.0
	v_rcp_f32_e32 v5, v3
	v_cvt_pk_bf16_f32 v4, v2, s0
	v_lshl_or_b32 v2, v21, 8, v20
	v_ashrrev_i32_e32 v3, 31, v2
	v_lshlrev_b32_e32 v2, 1, v2
	ds_write_b16 v2, v4
	v_fma_f32 v4, v5, -2.0, 1.0
	v_add_f32_e32 v5, v15, v15
	v_mul_f32_e32 v5, 0x3fb8aa3b, v5
	v_exp_f32_e32 v5, v5
	v_add_f32_e32 v15, v23, v23
	v_mul_f32_e32 v15, 0x3fb8aa3b, v15
	v_exp_f32_e32 v15, v15
	v_add_f32_e32 v5, 1.0, v5
	v_rcp_f32_e32 v5, v5
	v_cvt_pk_bf16_f32 v4, v4, s0
	ds_write_b16 v2, v4 offset:512
	v_add_f32_e32 v4, 1.0, v15
	v_fma_f32 v5, v5, -2.0, 1.0
	v_cvt_pk_bf16_f32 v5, v5, s0
	ds_write_b16 v2, v5 offset:1024
	v_add_f32_e32 v5, v24, v24
	v_mul_f32_e32 v5, 0x3fb8aa3b, v5
	v_exp_f32_e32 v5, v5
	v_rcp_f32_e32 v4, v4
	v_add_f32_e32 v15, v17, v17
	v_mul_f32_e32 v15, 0x3fb8aa3b, v15
	v_add_f32_e32 v5, 1.0, v5
	v_rcp_f32_e32 v5, v5
	v_exp_f32_e32 v15, v15
	v_fma_f32 v4, v4, -2.0, 1.0
	v_cvt_pk_bf16_f32 v4, v4, s0
	v_fma_f32 v5, v5, -2.0, 1.0
	ds_write_b16 v2, v4 offset:1536
	v_add_f32_e32 v4, 1.0, v15
	v_cvt_pk_bf16_f32 v5, v5, s0
	v_rcp_f32_e32 v4, v4
	ds_write_b16 v2, v5 offset:2048
	v_add_f32_e32 v5, v31, v31
	v_add_f32_e32 v15, v33, v33
	v_mul_f32_e32 v5, 0x3fb8aa3b, v5
	v_mul_f32_e32 v15, 0x3fb8aa3b, v15
	v_exp_f32_e32 v5, v5
	v_exp_f32_e32 v15, v15
	v_fma_f32 v4, v4, -2.0, 1.0
	v_cvt_pk_bf16_f32 v4, v4, s0
	v_add_f32_e32 v5, 1.0, v5
	ds_write_b16 v2, v4 offset:2560
	v_add_f32_e32 v4, 1.0, v15
	v_rcp_f32_e32 v5, v5
	v_rcp_f32_e32 v4, v4
	v_lshlrev_b32_e32 v7, 16, v7
	v_lshlrev_b32_e32 v9, 16, v9
	v_fma_f32 v5, v5, -2.0, 1.0
	v_fma_f32 v4, v4, -2.0, 1.0
	v_cvt_pk_bf16_f32 v5, v5, s0
	v_cvt_pk_bf16_f32 v15, v4, s0
	v_or3_b32 v4, v1, v20, s14
	ds_write_b16 v2, v5 offset:3072
	v_ashrrev_i32_e32 v5, 31, v4
	v_lshlrev_b32_e32 v4, 1, v4
	s_waitcnt vmcnt(11)
; __device__ __forceinline__ bf16_t f2bf(float f) { return (bf16_t)(pk2(f, 0.f) & 0xffffu); }
; __device__ __forceinline__ float sigmoidf_(float x) { return frcp(1.0f + __expf(-x)); }
; __device__ __forceinline__ float tanhf_(float x) { return 1.0f - 2.0f * frcp(1.0f + __expf(2.0f * x)); }
; __device__ __forceinline__ void rwkv_phase_a(const Ctx& C) {
;     ...
;           zmix8(r0, pz, m0, t8);
; #pragma unroll
;           for (int u = 0; u < 8; ++u) scrg[(tg8 * 8 + u) * 256 + ci] = f2bf(tanhf_(t8[u]));
;           zmix8(r1, pz, m1, t8);
; #pragma unroll
;           for (int u = 0; u < 8; ++u) scrg[(tg8 * 8 + u) * 256 + 64 + ci] = f2bf(t8[u]);
;           zmix8(r2, pz, m2, t8);
; #pragma unroll
;           for (int u = 0; u < 8; ++u) scrg[(tg8 * 8 + u) * 256 + 128 + ci] = f2bf(sigmoidf_(t8[u]));
;           zmix8(r3, pz, m3, t8);
; #pragma unroll
;           for (int u = 0; u < 8; ++u) scrg[(tg8 * 8 + u) * 256 + 192 + ci] = f2bf(sigmoidf_(t8[u]));
;           asm volatile("s_waitcnt vmcnt(0)" ::: "memory");
;           __syncthreads();
;           __builtin_amdgcn_fence(__ATOMIC_ACQUIRE, "agent");
;           asm volatile("s_waitcnt vmcnt(0)" ::: "memory");
;       }
;       bf16x8 Af[4][2], Bf[4][2][2]; bf16_t zn[3][9];
;       {
;           int tid = C.tid; asm volatile("" : "+v"(tid));
;           const int lane = tid & 63, q = lane >> 4, l15 = lane & 15, mrow = mt * 16 + l15, nc0 = nt0 * 16 + l15, ci = tid & 63, tokb = tok0 + (tid >> 6) * 8;
; #pragma unroll
;           for (int g = 0; g < 4; ++g)
; #pragma unroll
;               for (int ks = 0; ks < 2; ++ks) Af[g][ks] = *(const bf16x8*)(scrg + (size_t)mrow * 256 + g * 64 + ks * 32 + q * 8);
	v_lshlrev_b32_e32 v1, 16, v43
	ds_write_b16 v4, v15
	v_fma_f32 v1, v22, v1, -v11
	v_lshlrev_b32_e32 v15, 16, v36
	v_sub_f32_e32 v17, v11, v15
	v_fmac_f32_e32 v11, v1, v34
	v_lshlrev_b32_e32 v1, 16, v37
	v_sub_f32_e32 v20, v15, v1
	v_fmac_f32_e32 v15, v17, v34
	v_sub_f32_e32 v17, v1, v7
	v_fmac_f32_e32 v1, v20, v34
	v_sub_f32_e32 v20, v7, v9
	v_fmac_f32_e32 v7, v17, v34
	s_waitcnt vmcnt(8)
	v_lshlrev_b32_e32 v17, 16, v25
	v_cvt_pk_bf16_f32 v1, v1, s0
	v_sub_f32_e32 v21, v9, v17
	v_fmac_f32_e32 v9, v20, v34
	s_waitcnt vmcnt(7)
	v_lshlrev_b32_e32 v20, 16, v26
	ds_write_b16 v2, v1 offset:1152
	v_cvt_pk_bf16_f32 v1, v7, s0
	v_sub_f32_e32 v23, v17, v20
	v_fmac_f32_e32 v17, v21, v34
	s_waitcnt vmcnt(2)
	v_lshlrev_b32_e32 v19, 16, v19
	ds_write_b16 v2, v1 offset:1664
	v_cvt_pk_bf16_f32 v1, v9, s0
	v_sub_f32_e32 v21, v20, v19
	v_fmac_f32_e32 v20, v23, v34
	ds_write_b16 v2, v1 offset:2176
	v_cvt_pk_bf16_f32 v1, v17, s0
	v_fmac_f32_e32 v19, v21, v34
	v_cvt_pk_bf16_f32 v11, v11, s0
	ds_write_b16 v2, v1 offset:2688
	v_cvt_pk_bf16_f32 v1, v20, s0
	ds_write_b16 v2, v11 offset:128
	v_cvt_pk_bf16_f32 v11, v15, s0
	ds_write_b16 v2, v1 offset:3200
	v_cvt_pk_bf16_f32 v1, v19, s0
	ds_write_b16 v2, v11 offset:640
	ds_write_b16 v4, v1 offset:128
	v_lshlrev_b32_e32 v1, 16, v44
	v_lshlrev_b32_e32 v7, 16, v13
	v_fma_f32 v1, v22, v1, -v7
	v_lshlrev_b32_e32 v9, 16, v38
	v_sub_f32_e32 v11, v7, v9
	v_fmac_f32_e32 v7, v1, v35
	v_lshlrev_b32_e32 v1, 16, v39
	v_sub_f32_e32 v13, v9, v1
	v_fmac_f32_e32 v9, v11, v35
	v_mul_f32_e32 v7, 0xbfb8aa3b, v7
	v_exp_f32_e32 v7, v7
	v_mul_f32_e32 v9, 0xbfb8aa3b, v9
	v_exp_f32_e32 v9, v9
	v_lshlrev_b32_e32 v11, 16, v40
	v_add_f32_e32 v7, 1.0, v7
	v_rcp_f32_e32 v7, v7
	v_add_f32_e32 v9, 1.0, v9
	v_rcp_f32_e32 v9, v9
	v_sub_f32_e32 v15, v1, v11
	v_fmac_f32_e32 v1, v13, v35
	v_lshlrev_b32_e32 v13, 16, v41
	v_sub_f32_e32 v17, v11, v13
	v_fmac_f32_e32 v11, v15, v35
	v_cvt_pk_bf16_f32 v7, v7, s0
	v_mul_f32_e32 v1, 0xbfb8aa3b, v1
	ds_write_b16 v2, v7 offset:256
	v_cvt_pk_bf16_f32 v7, v9, s0
	v_exp_f32_e32 v1, v1
	v_mul_f32_e32 v9, 0xbfb8aa3b, v11
	v_exp_f32_e32 v9, v9
	v_lshlrev_b32_e32 v15, 16, v27
	v_sub_f32_e32 v19, v13, v15
	v_fmac_f32_e32 v13, v17, v35
	v_add_f32_e32 v1, 1.0, v1
	ds_write_b16 v2, v7 offset:768
	v_rcp_f32_e32 v1, v1
	v_add_f32_e32 v7, 1.0, v9
	v_mul_f32_e32 v9, 0xbfb8aa3b, v13
	v_rcp_f32_e32 v7, v7
	v_exp_f32_e32 v9, v9
	v_lshlrev_b32_e32 v17, 16, v29
	v_cvt_pk_bf16_f32 v1, v1, s0
	v_sub_f32_e32 v20, v15, v17
	v_fmac_f32_e32 v15, v19, v35
	ds_write_b16 v2, v1 offset:1280
	v_cvt_pk_bf16_f32 v1, v7, s0
	v_add_f32_e32 v7, 1.0, v9
	v_rcp_f32_e32 v7, v7
	v_mul_f32_e32 v9, 0xbfb8aa3b, v15
	v_exp_f32_e32 v9, v9
	s_waitcnt vmcnt(1)
	v_lshlrev_b32_e32 v19, 16, v45
	v_sub_f32_e32 v21, v17, v19
	v_fmac_f32_e32 v17, v20, v35
	v_fmac_f32_e32 v19, v21, v35
	ds_write_b16 v2, v1 offset:1792
	v_cvt_pk_bf16_f32 v1, v7, s0
	v_mul_f32_e32 v7, 0xbfb8aa3b, v17
	ds_write_b16 v2, v1 offset:2304
	v_add_f32_e32 v1, 1.0, v9
	v_exp_f32_e32 v7, v7
	v_mul_f32_e32 v9, 0xbfb8aa3b, v19
	v_exp_f32_e32 v9, v9
	v_rcp_f32_e32 v1, v1
	v_add_f32_e32 v7, 1.0, v7
	v_rcp_f32_e32 v7, v7
	v_add_f32_e32 v9, 1.0, v9
	v_rcp_f32_e32 v9, v9
	v_cvt_pk_bf16_f32 v1, v1, s0
	ds_write_b16 v2, v1 offset:2816
	v_cvt_pk_bf16_f32 v1, v7, s0
	ds_write_b16 v2, v1 offset:3328
	v_cvt_pk_bf16_f32 v1, v9, s0
	ds_write_b16 v4, v1 offset:256
	v_lshlrev_b32_e32 v1, 16, v14
	v_lshlrev_b32_e32 v7, 16, v42
	v_fma_f32 v1, v22, v1, -v7
	v_lshlrev_b32_e32 v6, 16, v6
	v_sub_f32_e32 v9, v7, v6
	v_fmac_f32_e32 v7, v1, v28
	v_mul_f32_e32 v7, 0xbfb8aa3b, v7
	v_exp_f32_e32 v7, v7
	v_lshlrev_b32_e32 v1, 16, v8
	v_sub_f32_e32 v8, v6, v1
	v_fmac_f32_e32 v6, v9, v28
	v_mul_f32_e32 v6, 0xbfb8aa3b, v6
	v_add_f32_e32 v7, 1.0, v7
	v_exp_f32_e32 v6, v6
	v_rcp_f32_e32 v7, v7
	v_lshlrev_b32_e32 v9, 16, v10
	v_sub_f32_e32 v10, v1, v9
	v_fmac_f32_e32 v1, v8, v28
	v_lshlrev_b32_e32 v8, 16, v12
	v_sub_f32_e32 v11, v9, v8
	v_fmac_f32_e32 v9, v10, v28
	v_add_f32_e32 v6, 1.0, v6
	v_cvt_pk_bf16_f32 v7, v7, s0
	v_mul_f32_e32 v1, 0xbfb8aa3b, v1
	v_rcp_f32_e32 v6, v6
	ds_write_b16 v2, v7 offset:384
	v_exp_f32_e32 v1, v1
	v_mul_f32_e32 v7, 0xbfb8aa3b, v9
	v_exp_f32_e32 v7, v7
	v_lshlrev_b32_e32 v10, 16, v16
	v_sub_f32_e32 v12, v8, v10
	v_fmac_f32_e32 v8, v11, v28
	v_cvt_pk_bf16_f32 v6, v6, s0
	v_add_f32_e32 v1, 1.0, v1
	ds_write_b16 v2, v6 offset:896
	v_rcp_f32_e32 v1, v1
	v_add_f32_e32 v6, 1.0, v7
	v_mul_f32_e32 v7, 0xbfb8aa3b, v8
	v_rcp_f32_e32 v6, v6
	v_exp_f32_e32 v7, v7
	v_lshlrev_b32_e32 v11, 16, v18
	v_cvt_pk_bf16_f32 v1, v1, s0
	v_sub_f32_e32 v13, v10, v11
	v_fmac_f32_e32 v10, v12, v28
	ds_write_b16 v2, v1 offset:1408
	v_cvt_pk_bf16_f32 v1, v6, s0
	v_add_f32_e32 v6, 1.0, v7
	v_rcp_f32_e32 v6, v6
	v_mul_f32_e32 v7, 0xbfb8aa3b, v10
	v_exp_f32_e32 v7, v7
	s_waitcnt vmcnt(0)
	v_lshlrev_b32_e32 v12, 16, v46
	v_sub_f32_e32 v14, v11, v12
	v_fmac_f32_e32 v11, v13, v28
	v_fmac_f32_e32 v12, v28, v14
	ds_write_b16 v2, v1 offset:1920
	v_cvt_pk_bf16_f32 v1, v6, s0
	v_mul_f32_e32 v6, 0xbfb8aa3b, v11
	ds_write_b16 v2, v1 offset:2432
	v_add_f32_e32 v1, 1.0, v7
	v_exp_f32_e32 v6, v6
	v_mul_f32_e32 v7, 0xbfb8aa3b, v12
	v_exp_f32_e32 v7, v7
	v_rcp_f32_e32 v1, v1
	v_add_f32_e32 v6, 1.0, v6
	v_rcp_f32_e32 v6, v6
	v_add_f32_e32 v7, 1.0, v7
	v_rcp_f32_e32 v7, v7
	v_cvt_pk_bf16_f32 v1, v1, s0
	ds_write_b16 v2, v1 offset:2944
	v_cvt_pk_bf16_f32 v1, v6, s0
	ds_write_b16 v2, v1 offset:3456
	v_cvt_pk_bf16_f32 v1, v7, s0
	ds_write_b16 v4, v1 offset:384
	v_mov_b32_e32 v1, v0
	s_waitcnt lgkmcnt(0)
	s_barrier
	v_and_b32_e32 v34, 15, v0
	v_or_b32_e32 v34, s3, v34
	v_and_b32_e32 v35, 48, v0
	v_lshl_or_b32 v34, v34, 9, v35
	ds_read_b128 v[2:5], v34
	ds_read_b128 v[6:9], v34 offset:64
	ds_read_b128 v[10:13], v34 offset:128
	ds_read_b128 v[14:17], v34 offset:192
	ds_read_b128 v[18:21], v34 offset:256
	ds_read_b128 v[22:25], v34 offset:320
	ds_read_b128 v[26:29], v34 offset:384
	ds_read_b128 v[30:33], v34 offset:448
	s_waitcnt lgkmcnt(0)
	s_barrier
	s_mov_b64 s[16:17], 0xf400000
	v_writelane_b32 v253, s20, 17
	s_waitcnt vmcnt(27)
	v_perm_b32 v229, v60, v59, s1
	s_waitcnt vmcnt(25)
	v_perm_b32 v219, v62, v68, s1
	v_perm_b32 v221, v57, v56, s1
	s_waitcnt vmcnt(23)
	v_perm_b32 v228, v64, v63, s1
	s_waitcnt vmcnt(21)
	v_perm_b32 v217, v71, v69, s1
	s_waitcnt vmcnt(20)
	v_perm_b32 v227, v70, v61, s1
	s_waitcnt vmcnt(18)
	v_perm_b32 v225, v65, v72, s1
	s_waitcnt vmcnt(16)
	v_perm_b32 v226, v67, v66, s1
	s_waitcnt vmcnt(13)
	v_perm_b32 v213, v75, v73, s1
	s_waitcnt vmcnt(11)
	v_perm_b32 v224, v47, v74, s1
	s_waitcnt vmcnt(10)
	v_perm_b32 v220, v58, v49, s1
	s_waitcnt vmcnt(8)
	v_perm_b32 v218, v54, v52, s1
	s_waitcnt vmcnt(7)
	v_perm_b32 v215, v50, v48, s1
	s_branch .LBB0_717
